# LayerNorm loops (after w_out, after first FFN): modulation vectors loaded only when the row's batch changes (first row, sample row), kept in spare VGPRs and copied each iteration
# speedup vs baseline: 1.0130x; 1.0130x over previous
.LBB0_1221:
	s_cmp_lt_u32 s3, 8
	s_cselect_b32 s12, s10, s18
	s_add_i32 s92, s12, 0xffffc000
	s_lshr_b32 s9, s92, 2
	s_ashr_i32 s8, s12, 11
	s_add_i32 s9, s9, 8
	s_cmpk_lt_i32 s12, 0x4000
	s_cselect_b32 s8, s8, s9
	v_readlane_b32 s9, v255, 4
	s_add_i32 s8, s8, s9
	s_mul_hi_i32 s9, s8, 0x9000
	s_mul_i32 s8, s8, 0x9000
	s_add_u32 s8, s19, s8
	s_addc_u32 s9, s20, s9
	s_add_u32 s14, s8, 0x1000
	s_addc_u32 s15, s9, 0
	s_cmp_eq_u32 s3, 0
	s_cbranch_scc1 .Lmy_lnh_a_reload
	s_cmp_lg_u32 s3, 8
	s_cbranch_scc1 .Lmy_lnh_a_copy
.Lmy_lnh_a_reload:
	global_load_dwordx4 v[178:181], v144, s[8:9]
	global_load_dwordx4 v[182:185], v144, s[8:9] offset:1024
	global_load_dwordx4 v[186:189], v144, s[14:15]
	global_load_dwordx4 v[190:193], v159, s[14:15]
	global_load_dwordx4 v[212:215], v144, s[8:9] offset:2048
	global_load_dwordx4 v[216:219], v144, s[8:9] offset:3072
	global_load_dwordx4 v[222:225], v160, s[14:15]
	global_load_dwordx4 v[226:229], v161, s[14:15]
	s_waitcnt vmcnt(0)
.Lmy_lnh_a_copy:
	v_mov_b64_e32 v[92:93], v[178:179]
	v_mov_b64_e32 v[94:95], v[180:181]
	v_mov_b64_e32 v[80:81], v[182:183]
	v_mov_b64_e32 v[82:83], v[184:185]
	v_mov_b64_e32 v[96:97], v[186:187]
	v_mov_b64_e32 v[98:99], v[188:189]
	v_mov_b64_e32 v[84:85], v[190:191]
	v_mov_b64_e32 v[86:87], v[192:193]
	v_mov_b64_e32 v[72:73], v[212:213]
	v_mov_b64_e32 v[74:75], v[214:215]
	v_mov_b64_e32 v[64:65], v[216:217]
	v_mov_b64_e32 v[66:67], v[218:219]
	v_mov_b64_e32 v[76:77], v[222:223]
	v_mov_b64_e32 v[78:79], v[224:225]
	v_mov_b64_e32 v[68:69], v[226:227]
	v_mov_b64_e32 v[70:71], v[228:229]
	s_waitcnt vmcnt(4)
	v_mov_b64_e32 v[50:51], v[46:47]
	v_mov_b64_e32 v[54:55], v[42:43]
	v_mov_b64_e32 v[58:59], v[34:35]
	s_add_i32 s8, s3, 2
	v_mov_b64_e32 v[62:63], v[38:39]
	v_mov_b64_e32 v[48:49], v[44:45]
	v_mov_b64_e32 v[52:53], v[40:41]
	v_mov_b64_e32 v[56:57], v[32:33]
	s_cmp_ge_u32 s8, s11
	v_mov_b64_e32 v[60:61], v[36:37]
	s_cbranch_scc1 .Lmy_lnA_noprefetch
	s_add_i32 s8, s10, 0x200
	s_cmp_lt_u32 s3, 6
	s_cselect_b32 s8, s8, s18
	s_ashr_i32 s9, s8, 31
	s_lshl_b64 s[8:9], s[8:9], 12
	v_lshl_add_u64 v[44:45], v[154:155], 0, s[8:9]
	global_load_dwordx4 v[36:39], v[44:45], off
	global_load_dwordx4 v[32:35], v[44:45], off offset:1024
	global_load_dwordx4 v[40:43], v[44:45], off offset:2048
	s_nop 0
	global_load_dwordx4 v[44:47], v[44:45], off offset:3072
	s_branch .LBB0_1223

.LBB0_1470:
	s_lshl_b32 s8, s3, 8
	s_add_i32 s8, s8, s12
	s_cmp_lt_u32 s3, 8
	s_cselect_b32 s14, s8, s20
	s_add_i32 s92, s14, 0xffffc000
	s_lshr_b32 s9, s92, 2
	s_ashr_i32 s8, s14, 11
	s_add_i32 s9, s9, 8
	s_cmpk_lt_i32 s14, 0x4000
	s_cselect_b32 s8, s8, s9
	v_readlane_b32 s9, v255, 4
	s_add_i32 s8, s8, s9
	s_mul_hi_i32 s9, s8, 0x9000
	s_mul_i32 s8, s8, 0x9000
	s_add_u32 s8, s21, s8
	s_addc_u32 s9, s22, s9
	s_add_u32 s16, s8, 0x1000
	s_addc_u32 s17, s9, 0
	s_cmp_eq_u32 s3, 0
	s_cbranch_scc1 .Lmy_lnh_b_reload
	s_cmp_lg_u32 s3, 8
	s_cbranch_scc1 .Lmy_lnh_b_copy
.Lmy_lnh_b_reload:
	global_load_dwordx4 v[178:181], v130, s[8:9]
	global_load_dwordx4 v[182:185], v130, s[8:9] offset:1024
	global_load_dwordx4 v[186:189], v130, s[16:17]
	global_load_dwordx4 v[190:193], v131, s[16:17]
	global_load_dwordx4 v[212:215], v130, s[8:9] offset:2048
	global_load_dwordx4 v[216:219], v130, s[8:9] offset:3072
	global_load_dwordx4 v[222:225], v132, s[16:17]
	global_load_dwordx4 v[226:229], v133, s[16:17]
	s_waitcnt vmcnt(0)
.Lmy_lnh_b_copy:
	v_mov_b64_e32 v[92:93], v[178:179]
	v_mov_b64_e32 v[94:95], v[180:181]
	v_mov_b64_e32 v[80:81], v[182:183]
	v_mov_b64_e32 v[82:83], v[184:185]
	v_mov_b64_e32 v[96:97], v[186:187]
	v_mov_b64_e32 v[98:99], v[188:189]
	v_mov_b64_e32 v[84:85], v[190:191]
	v_mov_b64_e32 v[86:87], v[192:193]
	v_mov_b64_e32 v[72:73], v[212:213]
	v_mov_b64_e32 v[74:75], v[214:215]
	v_mov_b64_e32 v[64:65], v[216:217]
	v_mov_b64_e32 v[66:67], v[218:219]
	v_mov_b64_e32 v[76:77], v[222:223]
	v_mov_b64_e32 v[78:79], v[224:225]
	v_mov_b64_e32 v[68:69], v[226:227]
	v_mov_b64_e32 v[70:71], v[228:229]
	s_waitcnt vmcnt(4)
	v_mov_b64_e32 v[50:51], v[46:47]
	v_mov_b64_e32 v[54:55], v[42:43]
	v_mov_b64_e32 v[58:59], v[34:35]
	s_add_i32 s8, s3, 2
	v_mov_b64_e32 v[62:63], v[38:39]
	v_mov_b64_e32 v[48:49], v[44:45]
	v_mov_b64_e32 v[52:53], v[40:41]
	v_mov_b64_e32 v[56:57], v[32:33]
	s_cmp_ge_u32 s8, s13
	v_mov_b64_e32 v[60:61], v[36:37]
	s_cbranch_scc1 .Lmy_lnB_noprefetch
	s_lshl_b32 s8, s8, 8
	s_add_i32 s8, s8, s12
	s_cmp_lt_u32 s3, 6
	s_cselect_b32 s8, s8, s20
	s_ashr_i32 s9, s8, 31
	s_lshl_b64 s[8:9], s[8:9], 12
	v_lshl_add_u64 v[44:45], v[120:121], 0, s[8:9]
	global_load_dwordx4 v[36:39], v[44:45], off
	global_load_dwordx4 v[32:35], v[44:45], off offset:1024
	global_load_dwordx4 v[40:43], v[44:45], off offset:2048
	s_nop 0
	global_load_dwordx4 v[44:47], v[44:45], off offset:3072
	s_branch .LBB0_1472
